# LDS-DMA issue rebalanced 4/4/4/4 per phase in P1+P5 K-loops (on top of v1)
# speedup vs baseline: 1.0113x; 1.0066x over previous
; #define PG8_STAGE(bufoff, gbase, voff) do { _Pragma("unroll") for (int _i = 0; _i < 2; ++_i) \
;         __builtin_amdgcn_global_load_lds((const __attribute__((address_space(1))) unsigned*)((const char*)(gbase) + (voff)[_i]), (LAS unsigned*)(lds + (bufoff) + ldsw + _i * 8192), 16, 0, 0); } while (0)
; #define PG8_LDA(dst, b, h) do { _Pragma("unroll") for (int m = 0; m < 4; ++m) _Pragma("unroll") for (int k = 0; k < 2; ++k) dst[m][k] = *(const LAS bf16x8*)(lds + PG8_SA(b, h) + aoff + m * 2048 + k * 1024); } while (0)
; #define PG8_LDB(dst, b, h) do { _Pragma("unroll") for (int n = 0; n < 2; ++n) _Pragma("unroll") for (int k = 0; k < 2; ++k) dst[n][k] = *(const LAS bf16x8*)(lds + PG8_SB(b, h) + boff + n * 2048 + k * 1024); } while (0)
; #define PG8_MMA(ai, bj, At, Bt) do { __builtin_amdgcn_s_setprio(1); _Pragma("unroll") for (int m = 0; m < 4; ++m) _Pragma("unroll") for (int n = 0; n < 2; ++n) _Pragma("unroll") for (int k = 0; k < 2; ++k) \
;         acc[ai][bj][m][n] = __builtin_amdgcn_mfma_f32_16x16x32_bf16(Bt[n][k], At[m][k], acc[ai][bj][m][n], 0, 0, 0); __builtin_amdgcn_s_setprio(0); } while (0)
; #define PG8_WAIT_V(n) asm volatile("s_waitcnt vmcnt(" #n ")" ::: "memory")
; template <class Epi, class SchedT, bool ALIGN_EPI, bool SP2>
; __device__ __forceinline__ void gemm_phase(LAS unsigned char* lds, const int ldk, const int nt, const SchedT& S, const Epi& E) {
;     ...
;         for (int t = 0; t < nt; t += 2) {
;             const bool last = (t == nt - 2);
;             const char* a1 = cA + (size_t)(t + 1) * kstep;
;             const char* a2 = last ? nA : cA + (size_t)(t + 2) * kstep; const char* b2 = last ? nB : cB + (size_t)(t + 2) * kstep;
;             const char* a3 = a2 + kstep; const char* b3 = b2 + kstep;
;             if constexpr (SP2) {
;             PG8_LDB(B0, 0, 0); PG8_LDB(B1, 0, 1); PG8_SCHED; PG8_LDA(At, 0, 0); PG8_STAGE(PG8_SA(1, 1), a1 + hstep, voffA);
;             PG8_WAIT_V(8); PG8_WAIT_L(0); PG8_BAR; PG8_MMA(0, 0, At, B0); PG8_MMA(0, 1, At, B1); PG8_BAR; PG8_SCHED;
;     ...
;         for (int a = 0; a < 2; ++a)
; #pragma unroll
;             for (int b = 0; b < 2; ++b)
; #pragma unroll
;                 for (int m = 0; m < 4; ++m)
; #pragma unroll
;                     for (int n = 0; n < 2; ++n) acc[a][b][m][n] = (f32x4){0.f, 0.f, 0.f, 0.f};
;         }
;         cur = nxt; cA = nA; cB = nB; ++ui;
.LBB0_122:
	s_add_u32 s0, s12, 0x80080
	s_addc_u32 s1, s13, 0
	s_add_u32 s18, s16, 0x100
	v_mov_b32_e32 v4, 0
	s_addc_u32 s19, s17, 0
	s_mov_b32 s21, -2
	v_mov_b32_e32 v5, v4
	v_mov_b32_e32 v6, v4
	v_mov_b32_e32 v7, v4
	v_mov_b32_e32 v8, v4
	v_mov_b32_e32 v9, v4
	v_mov_b32_e32 v10, v4
	v_mov_b32_e32 v11, v4
	v_mov_b32_e32 v20, v4
	v_mov_b32_e32 v21, v4
	v_mov_b32_e32 v22, v4
	v_mov_b32_e32 v23, v4
	v_mov_b32_e32 v24, v4
	v_mov_b32_e32 v25, v4
	v_mov_b32_e32 v26, v4
	v_mov_b32_e32 v27, v4
	v_mov_b32_e32 v36, v4
	v_mov_b32_e32 v37, v4
	v_mov_b32_e32 v38, v4
	v_mov_b32_e32 v39, v4
	v_mov_b32_e32 v40, v4
	v_mov_b32_e32 v41, v4
	v_mov_b32_e32 v42, v4
	v_mov_b32_e32 v43, v4
	v_mov_b32_e32 v52, v4
	v_mov_b32_e32 v53, v4
	v_mov_b32_e32 v54, v4
	v_mov_b32_e32 v55, v4
	v_mov_b32_e32 v56, v4
	v_mov_b32_e32 v57, v4
	v_mov_b32_e32 v58, v4
	v_mov_b32_e32 v59, v4
	v_mov_b32_e32 v12, v4
	v_mov_b32_e32 v13, v4
	v_mov_b32_e32 v14, v4
	v_mov_b32_e32 v15, v4
	v_mov_b32_e32 v16, v4
	v_mov_b32_e32 v17, v4
	v_mov_b32_e32 v18, v4
	v_mov_b32_e32 v19, v4
	v_mov_b32_e32 v28, v4
	v_mov_b32_e32 v29, v4
	v_mov_b32_e32 v30, v4
	v_mov_b32_e32 v31, v4
	v_mov_b32_e32 v32, v4
	v_mov_b32_e32 v33, v4
	v_mov_b32_e32 v34, v4
	v_mov_b32_e32 v35, v4
	v_mov_b32_e32 v44, v4
	v_mov_b32_e32 v45, v4
	v_mov_b32_e32 v46, v4
	v_mov_b32_e32 v47, v4
	v_mov_b32_e32 v48, v4
	v_mov_b32_e32 v49, v4
	v_mov_b32_e32 v50, v4
	v_mov_b32_e32 v51, v4
	v_mov_b32_e32 v60, v4
	v_mov_b32_e32 v61, v4
	v_mov_b32_e32 v62, v4
	v_mov_b32_e32 v63, v4
	v_mov_b32_e32 v64, v4
	v_mov_b32_e32 v65, v4
	v_mov_b32_e32 v66, v4
	v_mov_b32_e32 v67, v4
	v_mov_b32_e32 v68, v4
	v_mov_b32_e32 v69, v4
	v_mov_b32_e32 v70, v4
	v_mov_b32_e32 v71, v4
	v_mov_b32_e32 v72, v4
	v_mov_b32_e32 v73, v4
	v_mov_b32_e32 v74, v4
	v_mov_b32_e32 v75, v4
	v_mov_b32_e32 v84, v4
	v_mov_b32_e32 v85, v4
	v_mov_b32_e32 v86, v4
	v_mov_b32_e32 v87, v4
	v_mov_b32_e32 v88, v4
	v_mov_b32_e32 v89, v4
	v_mov_b32_e32 v90, v4
	v_mov_b32_e32 v91, v4
	v_mov_b32_e32 v100, v4
	v_mov_b32_e32 v101, v4
	v_mov_b32_e32 v102, v4
	v_mov_b32_e32 v103, v4
	v_mov_b32_e32 v104, v4
	v_mov_b32_e32 v105, v4
	v_mov_b32_e32 v106, v4
	v_mov_b32_e32 v107, v4
	v_mov_b32_e32 v116, v4
	v_mov_b32_e32 v117, v4
	v_mov_b32_e32 v118, v4
	v_mov_b32_e32 v119, v4
	v_mov_b32_e32 v120, v4
	v_mov_b32_e32 v121, v4
	v_mov_b32_e32 v122, v4
	v_mov_b32_e32 v123, v4
	v_mov_b32_e32 v76, v4
	v_mov_b32_e32 v77, v4
	v_mov_b32_e32 v78, v4
	v_mov_b32_e32 v79, v4
	v_mov_b32_e32 v80, v4
	v_mov_b32_e32 v81, v4
	v_mov_b32_e32 v82, v4
	v_mov_b32_e32 v83, v4
	v_mov_b32_e32 v92, v4
	v_mov_b32_e32 v93, v4
	v_mov_b32_e32 v94, v4
	v_mov_b32_e32 v95, v4
	v_mov_b32_e32 v96, v4
	v_mov_b32_e32 v97, v4
	v_mov_b32_e32 v98, v4
	v_mov_b32_e32 v99, v4
	v_mov_b32_e32 v108, v4
	v_mov_b32_e32 v109, v4
	v_mov_b32_e32 v110, v4
	v_mov_b32_e32 v111, v4
	v_mov_b32_e32 v112, v4
	v_mov_b32_e32 v113, v4
	v_mov_b32_e32 v114, v4
	v_mov_b32_e32 v115, v4
	v_mov_b32_e32 v124, v4
	v_mov_b32_e32 v125, v4
	v_mov_b32_e32 v126, v4
	v_mov_b32_e32 v127, v4
	v_mov_b32_e32 v128, v4
	v_mov_b32_e32 v129, v4
	v_mov_b32_e32 v130, v4
	v_mov_b32_e32 v131, v4
	s_add_u32 s12, s0, 0xfff7ff80
	s_addc_u32 s13, s1, -1
	v_lshl_add_u64 v[236:237], s[12:13], 0, v[156:157]
	v_lshl_add_u64 v[238:239], s[12:13], 0, v[160:161]
.LBB0_123:
	s_add_u32 s12, s0, 0xfff80080
	s_addc_u32 s13, s1, -1
	s_add_i32 s34, 0, 0x10000
	s_cmp_eq_u32 s21, 28
	s_cselect_b32 s17, s61, s13
	s_cselect_b32 s16, s60, s12
	v_add_u32_e32 v0, s34, v212
	s_cselect_b32 s13, s31, s19
	s_cselect_b32 s12, s30, s18
	s_add_i32 s38, 0, 0x14000
	s_waitcnt lgkmcnt(0)
	ds_read_b128 v[132:135], v0
	ds_read_b128 v[136:139], v0 offset:1024
	ds_read_b128 v[140:143], v0 offset:2048
	ds_read_b128 v[144:147], v0 offset:3072
	v_add_u32_e32 v0, s38, v212
	ds_read_b128 v[148:151], v0
	ds_read_b128 v[152:155], v0 offset:1024
	ds_read_b128 v[184:187], v0 offset:2048
	ds_read_b128 v[188:191], v0 offset:3072
	v_lshl_add_u64 v[2:3], v[236:237], 0, s[24:25]
	s_mov_b32 m0, s92
	s_nop 0
	global_load_lds_dwordx4 v[2:3], off
	v_lshl_add_u64 v[2:3], v[238:239], 0, s[24:25]
	s_mov_b32 m0, s93
	s_nop 0
	global_load_lds_dwordx4 v[2:3], off
	v_lshl_add_u64 v[2:3], s[0:1], 0, v[180:181]
	s_add_i32 m0, s88, 0xc000
	ds_read_b128 v[192:195], v216
	ds_read_b128 v[196:199], v216 offset:1024
	ds_read_b128 v[200:203], v216 offset:2048
	ds_read_b128 v[204:207], v216 offset:3072
	ds_read_b128 v[218:221], v216 offset:4096
	ds_read_b128 v[222:225], v216 offset:5120
	ds_read_b128 v[226:229], v216 offset:6144
	ds_read_b128 v[230:233], v216 offset:7168
	global_load_lds_dwordx4 v[2:3], off
	v_lshl_add_u64 v[2:3], s[0:1], 0, v[182:183]
	s_add_i32 m0, s88, 0xe000
	s_nop 0
	global_load_lds_dwordx4 v[2:3], off
	s_waitcnt vmcnt(8)
	s_waitcnt lgkmcnt(0)
	s_barrier
; #define PG8_STAGE(bufoff, gbase, voff) do { _Pragma("unroll") for (int _i = 0; _i < 2; ++_i) \
;         __builtin_amdgcn_global_load_lds((const __attribute__((address_space(1))) unsigned*)((const char*)(gbase) + (voff)[_i]), (LAS unsigned*)(lds + (bufoff) + ldsw + _i * 8192), 16, 0, 0); } while (0)
; #define PG8_LDA(dst, b, h) do { _Pragma("unroll") for (int m = 0; m < 4; ++m) _Pragma("unroll") for (int k = 0; k < 2; ++k) dst[m][k] = *(const LAS bf16x8*)(lds + PG8_SA(b, h) + aoff + m * 2048 + k * 1024); } while (0)
; #define PG8_MMA(ai, bj, At, Bt) do { __builtin_amdgcn_s_setprio(1); _Pragma("unroll") for (int m = 0; m < 4; ++m) _Pragma("unroll") for (int n = 0; n < 2; ++n) _Pragma("unroll") for (int k = 0; k < 2; ++k) \
;         acc[ai][bj][m][n] = __builtin_amdgcn_mfma_f32_16x16x32_bf16(Bt[n][k], At[m][k], acc[ai][bj][m][n], 0, 0, 0); __builtin_amdgcn_s_setprio(0); } while (0)
; #define PG8_WAIT_V(n) asm volatile("s_waitcnt vmcnt(" #n ")" ::: "memory")
; #define PG8_WAIT_L(n) asm volatile("s_waitcnt lgkmcnt(" #n ")" ::: "memory")
; #define PG8_BAR __builtin_amdgcn_s_barrier()
; #define PG8_SCHED __builtin_amdgcn_sched_barrier(0)
; template <class Epi, class SchedT, bool ALIGN_EPI, bool SP2>
; __device__ __forceinline__ void gemm_phase(LAS unsigned char* lds, const int ldk, const int nt, const SchedT& S, const Epi& E) {
;     ...
;             PG8_WAIT_V(8); PG8_WAIT_L(0); PG8_BAR; PG8_MMA(0, 0, At, B0); PG8_MMA(0, 1, At, B1); PG8_BAR; PG8_SCHED;
;             PG8_LDA(At, 0, 1); PG8_STAGE(PG8_SB(0, 0), b2, voffB); PG8_STAGE(PG8_SB(0, 1), b2 + hstepB, voffB); PG8_STAGE(PG8_SA(0, 0), a2, voffA);
;             PG8_WAIT_V(8); PG8_WAIT_L(0); PG8_BAR; PG8_MMA(1, 0, At, B0); PG8_MMA(1, 1, At, B1); PG8_BAR; PG8_SCHED;
	s_setprio 1
	s_waitcnt lgkmcnt(0)
	v_mfma_f32_16x16x32_bf16 v[128:131], v[132:135], v[192:195], v[128:131]
	v_mfma_f32_16x16x32_bf16 v[124:127], v[140:143], v[192:195], v[124:127]
	v_mfma_f32_16x16x32_bf16 v[112:115], v[132:135], v[200:203], v[112:115]
	v_mfma_f32_16x16x32_bf16 v[108:111], v[140:143], v[200:203], v[108:111]
	v_mfma_f32_16x16x32_bf16 v[96:99], v[132:135], v[218:221], v[96:99]
	v_mfma_f32_16x16x32_bf16 v[92:95], v[140:143], v[218:221], v[92:95]
	v_mfma_f32_16x16x32_bf16 v[80:83], v[132:135], v[226:229], v[80:83]
	v_mfma_f32_16x16x32_bf16 v[76:79], v[140:143], v[226:229], v[76:79]
	v_mfma_f32_16x16x32_bf16 v[128:131], v[136:139], v[196:199], v[128:131]
	v_mfma_f32_16x16x32_bf16 v[124:127], v[144:147], v[196:199], v[124:127]
	v_mfma_f32_16x16x32_bf16 v[112:115], v[136:139], v[204:207], v[112:115]
	v_mfma_f32_16x16x32_bf16 v[108:111], v[144:147], v[204:207], v[108:111]
	v_mfma_f32_16x16x32_bf16 v[96:99], v[136:139], v[222:225], v[96:99]
	v_mfma_f32_16x16x32_bf16 v[92:95], v[144:147], v[222:225], v[92:95]
	v_mfma_f32_16x16x32_bf16 v[80:83], v[136:139], v[230:233], v[80:83]
	v_mfma_f32_16x16x32_bf16 v[76:79], v[144:147], v[230:233], v[76:79]
	s_setprio 0
	s_setprio 1
	v_mfma_f32_16x16x32_bf16 v[120:123], v[148:151], v[192:195], v[120:123]
	v_mfma_f32_16x16x32_bf16 v[116:119], v[184:187], v[192:195], v[116:119]
	v_mfma_f32_16x16x32_bf16 v[104:107], v[148:151], v[200:203], v[104:107]
	v_mfma_f32_16x16x32_bf16 v[100:103], v[184:187], v[200:203], v[100:103]
	v_mfma_f32_16x16x32_bf16 v[88:91], v[148:151], v[218:221], v[88:91]
	v_mfma_f32_16x16x32_bf16 v[84:87], v[184:187], v[218:221], v[84:87]
	v_mfma_f32_16x16x32_bf16 v[72:75], v[148:151], v[226:229], v[72:75]
	v_mfma_f32_16x16x32_bf16 v[68:71], v[184:187], v[226:229], v[68:71]
	v_mfma_f32_16x16x32_bf16 v[120:123], v[152:155], v[196:199], v[120:123]
	v_mfma_f32_16x16x32_bf16 v[116:119], v[188:191], v[196:199], v[116:119]
	v_mfma_f32_16x16x32_bf16 v[104:107], v[152:155], v[204:207], v[104:107]
	v_mfma_f32_16x16x32_bf16 v[100:103], v[188:191], v[204:207], v[100:103]
	v_mfma_f32_16x16x32_bf16 v[88:91], v[152:155], v[222:225], v[88:91]
	v_mfma_f32_16x16x32_bf16 v[84:87], v[188:191], v[222:225], v[84:87]
	v_mfma_f32_16x16x32_bf16 v[72:75], v[152:155], v[230:233], v[72:75]
	v_mfma_f32_16x16x32_bf16 v[68:71], v[188:191], v[230:233], v[68:71]
	s_setprio 0
	s_barrier
	s_add_i32 s34, s34, s87
	v_lshl_add_u64 v[208:209], s[12:13], 0, v[158:159]
	s_mov_b32 m0, s34
	ds_read_b128 v[192:195], v216 offset:16384
	ds_read_b128 v[196:199], v216 offset:17408
	ds_read_b128 v[200:203], v216 offset:18432
	ds_read_b128 v[204:207], v216 offset:19456
	ds_read_b128 v[218:221], v216 offset:20480
	ds_read_b128 v[222:225], v216 offset:21504
	ds_read_b128 v[226:229], v216 offset:22528
	ds_read_b128 v[230:233], v216 offset:23552
	global_load_lds_dwordx4 v[208:209], off
	s_add_i32 m0, s34, 0x2000
	s_add_u32 s34, s12, 0x20000
	v_lshl_add_u64 v[234:235], s[12:13], 0, v[174:175]
	s_addc_u32 s35, s13, 0
	s_add_i32 s38, s38, s87
	global_load_lds_dwordx4 v[234:235], off
	v_lshl_add_u64 v[2:3], s[34:35], 0, v[158:159]
	s_mov_b32 m0, s38
	v_lshl_add_u64 v[236:237], s[16:17], 0, v[156:157]
	global_load_lds_dwordx4 v[2:3], off
	v_lshl_add_u64 v[2:3], s[34:35], 0, v[174:175]
	s_add_i32 m0, s38, 0x2000
	v_lshl_add_u64 v[238:239], s[16:17], 0, v[160:161]
	global_load_lds_dwordx4 v[2:3], off
	s_waitcnt vmcnt(6)
	s_waitcnt lgkmcnt(0)
	s_barrier
	s_setprio 1
	s_waitcnt lgkmcnt(0)
	v_mfma_f32_16x16x32_bf16 v[64:67], v[132:135], v[192:195], v[64:67]
	v_mfma_f32_16x16x32_bf16 v[60:63], v[140:143], v[192:195], v[60:63]
	v_mfma_f32_16x16x32_bf16 v[48:51], v[132:135], v[200:203], v[48:51]
	v_mfma_f32_16x16x32_bf16 v[44:47], v[140:143], v[200:203], v[44:47]
	v_mfma_f32_16x16x32_bf16 v[32:35], v[132:135], v[218:221], v[32:35]
	v_mfma_f32_16x16x32_bf16 v[28:31], v[140:143], v[218:221], v[28:31]
	v_mfma_f32_16x16x32_bf16 v[16:19], v[132:135], v[226:229], v[16:19]
	v_mfma_f32_16x16x32_bf16 v[12:15], v[140:143], v[226:229], v[12:15]
	v_mfma_f32_16x16x32_bf16 v[64:67], v[136:139], v[196:199], v[64:67]
	v_mfma_f32_16x16x32_bf16 v[60:63], v[144:147], v[196:199], v[60:63]
	v_mfma_f32_16x16x32_bf16 v[48:51], v[136:139], v[204:207], v[48:51]
	v_mfma_f32_16x16x32_bf16 v[44:47], v[144:147], v[204:207], v[44:47]
	v_mfma_f32_16x16x32_bf16 v[32:35], v[136:139], v[222:225], v[32:35]
	v_mfma_f32_16x16x32_bf16 v[28:31], v[144:147], v[222:225], v[28:31]
	v_mfma_f32_16x16x32_bf16 v[16:19], v[136:139], v[230:233], v[16:19]
	v_mfma_f32_16x16x32_bf16 v[12:15], v[144:147], v[230:233], v[12:15]
	s_setprio 0
	s_setprio 1
	v_mfma_f32_16x16x32_bf16 v[56:59], v[148:151], v[192:195], v[56:59]
	v_mfma_f32_16x16x32_bf16 v[52:55], v[184:187], v[192:195], v[52:55]
	v_mfma_f32_16x16x32_bf16 v[40:43], v[148:151], v[200:203], v[40:43]
	v_mfma_f32_16x16x32_bf16 v[36:39], v[184:187], v[200:203], v[36:39]
	v_mfma_f32_16x16x32_bf16 v[24:27], v[148:151], v[218:221], v[24:27]
	v_mfma_f32_16x16x32_bf16 v[20:23], v[184:187], v[218:221], v[20:23]
	v_mfma_f32_16x16x32_bf16 v[8:11], v[148:151], v[226:229], v[8:11]
	v_mfma_f32_16x16x32_bf16 v[2:5], v[184:187], v[226:229], v[4:7]
	v_mfma_f32_16x16x32_bf16 v[56:59], v[152:155], v[196:199], v[56:59]
	v_mfma_f32_16x16x32_bf16 v[52:55], v[188:191], v[196:199], v[52:55]
	v_mfma_f32_16x16x32_bf16 v[40:43], v[152:155], v[204:207], v[40:43]
	v_mfma_f32_16x16x32_bf16 v[36:39], v[188:191], v[204:207], v[36:39]
	v_mfma_f32_16x16x32_bf16 v[24:27], v[152:155], v[222:225], v[24:27]
	v_mfma_f32_16x16x32_bf16 v[20:23], v[188:191], v[222:225], v[20:23]
	v_mfma_f32_16x16x32_bf16 v[8:11], v[152:155], v[230:233], v[8:11]
	v_mfma_f32_16x16x32_bf16 v[2:5], v[188:191], v[230:233], v[2:5]
	s_setprio 0
	s_barrier
; #define PG8_STAGE(bufoff, gbase, voff) do { _Pragma("unroll") for (int _i = 0; _i < 2; ++_i) \
;         __builtin_amdgcn_global_load_lds((const __attribute__((address_space(1))) unsigned*)((const char*)(gbase) + (voff)[_i]), (LAS unsigned*)(lds + (bufoff) + ldsw + _i * 8192), 16, 0, 0); } while (0)
; #define PG8_LDA(dst, b, h) do { _Pragma("unroll") for (int m = 0; m < 4; ++m) _Pragma("unroll") for (int k = 0; k < 2; ++k) dst[m][k] = *(const LAS bf16x8*)(lds + PG8_SA(b, h) + aoff + m * 2048 + k * 1024); } while (0)
; #define PG8_LDB(dst, b, h) do { _Pragma("unroll") for (int n = 0; n < 2; ++n) _Pragma("unroll") for (int k = 0; k < 2; ++k) dst[n][k] = *(const LAS bf16x8*)(lds + PG8_SB(b, h) + boff + n * 2048 + k * 1024); } while (0)
; #define PG8_MMA(ai, bj, At, Bt) do { __builtin_amdgcn_s_setprio(1); _Pragma("unroll") for (int m = 0; m < 4; ++m) _Pragma("unroll") for (int n = 0; n < 2; ++n) _Pragma("unroll") for (int k = 0; k < 2; ++k) \
;         acc[ai][bj][m][n] = __builtin_amdgcn_mfma_f32_16x16x32_bf16(Bt[n][k], At[m][k], acc[ai][bj][m][n], 0, 0, 0); __builtin_amdgcn_s_setprio(0); } while (0)
; #define PG8_WAIT_V(n) asm volatile("s_waitcnt vmcnt(" #n ")" ::: "memory")
; #define PG8_WAIT_L(n) asm volatile("s_waitcnt lgkmcnt(" #n ")" ::: "memory")
; #define PG8_BAR __builtin_amdgcn_s_barrier()
; #define PG8_SCHED __builtin_amdgcn_sched_barrier(0)
; template <class Epi, class SchedT, bool ALIGN_EPI, bool SP2>
; __device__ __forceinline__ void gemm_phase(LAS unsigned char* lds, const int ldk, const int nt, const SchedT& S, const Epi& E) {
;     ...
;             PG8_WAIT_V(8); PG8_WAIT_L(0); PG8_BAR; PG8_MMA(1, 0, At, B0); PG8_MMA(1, 1, At, B1); PG8_BAR; PG8_SCHED;
;             PG8_LDB(B0, 1, 0); PG8_LDB(B1, 1, 1); PG8_SCHED; PG8_LDA(At, 1, 0); PG8_STAGE(PG8_SA(0, 1), a2 + hstep, voffA);
;             PG8_WAIT_V(8); PG8_WAIT_L(0); PG8_BAR; PG8_MMA(0, 0, At, B0); PG8_MMA(0, 1, At, B1); PG8_BAR; PG8_SCHED;
	s_add_i32 s34, 0, 0x18000
	v_add_u32_e32 v0, s34, v212
	s_add_i32 s35, 0, 0x1c000
	ds_read_b128 v[132:135], v0
	ds_read_b128 v[136:139], v0 offset:1024
	ds_read_b128 v[140:143], v0 offset:2048
	ds_read_b128 v[144:147], v0 offset:3072
	v_add_u32_e32 v0, s35, v212
	ds_read_b128 v[148:151], v0
	ds_read_b128 v[152:155], v0 offset:1024
	ds_read_b128 v[184:187], v0 offset:2048
	ds_read_b128 v[188:191], v0 offset:3072
	s_add_u32 s16, s16, 0x80000
	s_addc_u32 s17, s17, 0
	s_mov_b32 m0, s88
	s_nop 0
	global_load_lds_dwordx4 v[236:237], off
	s_mov_b32 m0, s89
	s_nop 0
	global_load_lds_dwordx4 v[238:239], off
	s_mov_b32 m0, s90
	v_lshl_add_u64 v[6:7], s[16:17], 0, v[156:157]
	ds_read_b128 v[192:195], v216 offset:32768
	ds_read_b128 v[196:199], v216 offset:33792
	ds_read_b128 v[200:203], v216 offset:34816
	ds_read_b128 v[204:207], v216 offset:35840
	ds_read_b128 v[218:221], v216 offset:36864
	ds_read_b128 v[222:225], v216 offset:37888
	ds_read_b128 v[226:229], v216 offset:38912
	ds_read_b128 v[230:233], v216 offset:39936
	global_load_lds_dwordx4 v[6:7], off
	v_lshl_add_u64 v[6:7], s[16:17], 0, v[160:161]
	s_mov_b32 m0, s91
	s_nop 0
	global_load_lds_dwordx4 v[6:7], off
	s_waitcnt vmcnt(8)
	s_waitcnt lgkmcnt(0)
	s_barrier
	s_setprio 1
	s_waitcnt lgkmcnt(0)
	v_mfma_f32_16x16x32_bf16 v[128:131], v[132:135], v[192:195], v[128:131]
	v_mfma_f32_16x16x32_bf16 v[124:127], v[140:143], v[192:195], v[124:127]
	v_mfma_f32_16x16x32_bf16 v[112:115], v[132:135], v[200:203], v[112:115]
	v_mfma_f32_16x16x32_bf16 v[108:111], v[140:143], v[200:203], v[108:111]
	v_mfma_f32_16x16x32_bf16 v[96:99], v[132:135], v[218:221], v[96:99]
	v_mfma_f32_16x16x32_bf16 v[92:95], v[140:143], v[218:221], v[92:95]
	v_mfma_f32_16x16x32_bf16 v[80:83], v[132:135], v[226:229], v[80:83]
	v_mfma_f32_16x16x32_bf16 v[76:79], v[140:143], v[226:229], v[76:79]
	v_mfma_f32_16x16x32_bf16 v[128:131], v[136:139], v[196:199], v[128:131]
	v_mfma_f32_16x16x32_bf16 v[124:127], v[144:147], v[196:199], v[124:127]
	v_mfma_f32_16x16x32_bf16 v[112:115], v[136:139], v[204:207], v[112:115]
	v_mfma_f32_16x16x32_bf16 v[108:111], v[144:147], v[204:207], v[108:111]
	v_mfma_f32_16x16x32_bf16 v[96:99], v[136:139], v[222:225], v[96:99]
	v_mfma_f32_16x16x32_bf16 v[92:95], v[144:147], v[222:225], v[92:95]
	v_mfma_f32_16x16x32_bf16 v[80:83], v[136:139], v[230:233], v[80:83]
	v_mfma_f32_16x16x32_bf16 v[76:79], v[144:147], v[230:233], v[76:79]
	s_setprio 0
	s_setprio 1
	v_mfma_f32_16x16x32_bf16 v[120:123], v[148:151], v[192:195], v[120:123]
	v_mfma_f32_16x16x32_bf16 v[116:119], v[184:187], v[192:195], v[116:119]
	v_mfma_f32_16x16x32_bf16 v[104:107], v[148:151], v[200:203], v[104:107]
	v_mfma_f32_16x16x32_bf16 v[100:103], v[184:187], v[200:203], v[100:103]
	v_mfma_f32_16x16x32_bf16 v[88:91], v[148:151], v[218:221], v[88:91]
	v_mfma_f32_16x16x32_bf16 v[84:87], v[184:187], v[218:221], v[84:87]
	v_mfma_f32_16x16x32_bf16 v[72:75], v[148:151], v[226:229], v[72:75]
	v_mfma_f32_16x16x32_bf16 v[68:71], v[184:187], v[226:229], v[68:71]
	v_mfma_f32_16x16x32_bf16 v[120:123], v[152:155], v[196:199], v[120:123]
	v_mfma_f32_16x16x32_bf16 v[116:119], v[188:191], v[196:199], v[116:119]
	v_mfma_f32_16x16x32_bf16 v[104:107], v[152:155], v[204:207], v[104:107]
	v_mfma_f32_16x16x32_bf16 v[100:103], v[188:191], v[204:207], v[100:103]
	v_mfma_f32_16x16x32_bf16 v[88:91], v[152:155], v[222:225], v[88:91]
	v_mfma_f32_16x16x32_bf16 v[84:87], v[188:191], v[222:225], v[84:87]
	v_mfma_f32_16x16x32_bf16 v[72:75], v[152:155], v[230:233], v[72:75]
	v_mfma_f32_16x16x32_bf16 v[68:71], v[188:191], v[230:233], v[68:71]
	s_setprio 0
	s_barrier
; #define PG8_STAGE(bufoff, gbase, voff) do { _Pragma("unroll") for (int _i = 0; _i < 2; ++_i) \
;         __builtin_amdgcn_global_load_lds((const __attribute__((address_space(1))) unsigned*)((const char*)(gbase) + (voff)[_i]), (LAS unsigned*)(lds + (bufoff) + ldsw + _i * 8192), 16, 0, 0); } while (0)
; #define PG8_LDA(dst, b, h) do { _Pragma("unroll") for (int m = 0; m < 4; ++m) _Pragma("unroll") for (int k = 0; k < 2; ++k) dst[m][k] = *(const LAS bf16x8*)(lds + PG8_SA(b, h) + aoff + m * 2048 + k * 1024); } while (0)
; #define PG8_MMA(ai, bj, At, Bt) do { __builtin_amdgcn_s_setprio(1); _Pragma("unroll") for (int m = 0; m < 4; ++m) _Pragma("unroll") for (int n = 0; n < 2; ++n) _Pragma("unroll") for (int k = 0; k < 2; ++k) \
;         acc[ai][bj][m][n] = __builtin_amdgcn_mfma_f32_16x16x32_bf16(Bt[n][k], At[m][k], acc[ai][bj][m][n], 0, 0, 0); __builtin_amdgcn_s_setprio(0); } while (0)
; #define PG8_WAIT_V(n) asm volatile("s_waitcnt vmcnt(" #n ")" ::: "memory")
; #define PG8_WAIT_L(n) asm volatile("s_waitcnt lgkmcnt(" #n ")" ::: "memory")
; #define PG8_BAR __builtin_amdgcn_s_barrier()
; #define PG8_SCHED __builtin_amdgcn_sched_barrier(0)
; template <class Epi, class SchedT, bool ALIGN_EPI, bool SP2>
; __device__ __forceinline__ void gemm_phase(LAS unsigned char* lds, const int ldk, const int nt, const SchedT& S, const Epi& E) {
;     ...
;             PG8_WAIT_V(8); PG8_WAIT_L(0); PG8_BAR; PG8_MMA(0, 0, At, B0); PG8_MMA(0, 1, At, B1); PG8_BAR; PG8_SCHED;
;             PG8_LDA(At, 1, 1); PG8_STAGE(PG8_SB(1, 0), b3, voffB); PG8_STAGE(PG8_SB(1, 1), b3 + hstepB, voffB); PG8_STAGE(PG8_SA(1, 0), a3, voffA);
;             PG8_WAIT_V(8); PG8_WAIT_L(0); PG8_BAR; PG8_MMA(1, 0, At, B0); PG8_MMA(1, 1, At, B1); PG8_BAR; PG8_SCHED;
	s_add_i32 s16, s34, s87
	v_lshl_add_u64 v[6:7], v[208:209], 0, s[24:25]
	s_mov_b32 m0, s16
	ds_read_b128 v[192:195], v216 offset:49152
	ds_read_b128 v[196:199], v216 offset:50176
	ds_read_b128 v[200:203], v216 offset:51200
	ds_read_b128 v[204:207], v216 offset:52224
	ds_read_b128 v[218:221], v216 offset:53248
	ds_read_b128 v[222:225], v216 offset:54272
	ds_read_b128 v[226:229], v216 offset:55296
	ds_read_b128 v[230:233], v216 offset:56320
	global_load_lds_dwordx4 v[6:7], off
	s_add_i32 m0, s16, 0x2000
	s_add_u32 s12, s12, 0x20080
	v_lshl_add_u64 v[6:7], v[234:235], 0, s[24:25]
	s_addc_u32 s13, s13, 0
	s_add_i32 s16, s35, s87
	global_load_lds_dwordx4 v[6:7], off
	v_lshl_add_u64 v[6:7], s[12:13], 0, v[158:159]
	s_mov_b32 m0, s16
	s_nop 0
	global_load_lds_dwordx4 v[6:7], off
	v_lshl_add_u64 v[6:7], s[12:13], 0, v[174:175]
	s_add_i32 m0, s16, 0x2000
	s_nop 0
	global_load_lds_dwordx4 v[6:7], off
	s_waitcnt vmcnt(6)
	s_waitcnt lgkmcnt(0)
	s_barrier
	s_setprio 1
	s_waitcnt lgkmcnt(0)
	v_mfma_f32_16x16x32_bf16 v[64:67], v[132:135], v[192:195], v[64:67]
	v_mfma_f32_16x16x32_bf16 v[60:63], v[140:143], v[192:195], v[60:63]
	v_mfma_f32_16x16x32_bf16 v[48:51], v[132:135], v[200:203], v[48:51]
	v_mfma_f32_16x16x32_bf16 v[44:47], v[140:143], v[200:203], v[44:47]
	v_mfma_f32_16x16x32_bf16 v[32:35], v[132:135], v[218:221], v[32:35]
	v_mfma_f32_16x16x32_bf16 v[28:31], v[140:143], v[218:221], v[28:31]
	v_mfma_f32_16x16x32_bf16 v[16:19], v[132:135], v[226:229], v[16:19]
	v_mfma_f32_16x16x32_bf16 v[12:15], v[140:143], v[226:229], v[12:15]
	v_mfma_f32_16x16x32_bf16 v[64:67], v[136:139], v[196:199], v[64:67]
	v_mfma_f32_16x16x32_bf16 v[60:63], v[144:147], v[196:199], v[60:63]
	v_mfma_f32_16x16x32_bf16 v[48:51], v[136:139], v[204:207], v[48:51]
	v_mfma_f32_16x16x32_bf16 v[44:47], v[144:147], v[204:207], v[44:47]
	v_mfma_f32_16x16x32_bf16 v[32:35], v[136:139], v[222:225], v[32:35]
	v_mfma_f32_16x16x32_bf16 v[28:31], v[144:147], v[222:225], v[28:31]
	v_mfma_f32_16x16x32_bf16 v[16:19], v[136:139], v[230:233], v[16:19]
	v_mfma_f32_16x16x32_bf16 v[12:15], v[144:147], v[230:233], v[12:15]
	s_setprio 0
	s_setprio 1
	v_mfma_f32_16x16x32_bf16 v[56:59], v[148:151], v[192:195], v[56:59]
	v_mfma_f32_16x16x32_bf16 v[52:55], v[184:187], v[192:195], v[52:55]
	v_mfma_f32_16x16x32_bf16 v[40:43], v[148:151], v[200:203], v[40:43]
	v_mfma_f32_16x16x32_bf16 v[36:39], v[184:187], v[200:203], v[36:39]
	v_mfma_f32_16x16x32_bf16 v[24:27], v[148:151], v[218:221], v[24:27]
	v_mfma_f32_16x16x32_bf16 v[20:23], v[184:187], v[218:221], v[20:23]
	v_mfma_f32_16x16x32_bf16 v[6:9], v[148:151], v[226:229], v[8:11]
	v_mfma_f32_16x16x32_bf16 v[2:5], v[184:187], v[226:229], v[2:5]
	v_mfma_f32_16x16x32_bf16 v[56:59], v[152:155], v[196:199], v[56:59]
	v_mfma_f32_16x16x32_bf16 v[52:55], v[188:191], v[196:199], v[52:55]
	v_mfma_f32_16x16x32_bf16 v[40:43], v[152:155], v[204:207], v[40:43]
	v_mfma_f32_16x16x32_bf16 v[36:39], v[188:191], v[204:207], v[36:39]
	v_mfma_f32_16x16x32_bf16 v[24:27], v[152:155], v[222:225], v[24:27]
	v_mfma_f32_16x16x32_bf16 v[20:23], v[188:191], v[222:225], v[20:23]
	v_mfma_f32_16x16x32_bf16 v[8:11], v[152:155], v[230:233], v[6:9]
	v_mfma_f32_16x16x32_bf16 v[4:7], v[188:191], v[230:233], v[2:5]
	s_setprio 0
	s_barrier
	s_add_i32 s21, s21, 2
	s_add_u32 s0, s0, 0x100
	s_addc_u32 s1, s1, 0
	s_add_u32 s18, s18, 0x100
	s_addc_u32 s19, s19, 0
	s_cmp_gt_u32 s21, 29
	s_cbranch_scc0 .LBB0_123
	s_and_b64 vcc, exec, s[58:59]
	s_cbranch_vccz .LBB0_126
	s_barrier

; #define PG8_STAGE(bufoff, gbase, voff) do { _Pragma("unroll") for (int _i = 0; _i < 2; ++_i) \
;         __builtin_amdgcn_global_load_lds((const __attribute__((address_space(1))) unsigned*)((const char*)(gbase) + (voff)[_i]), (LAS unsigned*)(lds + (bufoff) + ldsw + _i * 8192), 16, 0, 0); } while (0)
; #define PG8_LDA(dst, b, h) do { _Pragma("unroll") for (int m = 0; m < 4; ++m) _Pragma("unroll") for (int k = 0; k < 2; ++k) dst[m][k] = *(const LAS bf16x8*)(lds + PG8_SA(b, h) + aoff + m * 2048 + k * 1024); } while (0)
; #define PG8_LDB(dst, b, h) do { _Pragma("unroll") for (int n = 0; n < 2; ++n) _Pragma("unroll") for (int k = 0; k < 2; ++k) dst[n][k] = *(const LAS bf16x8*)(lds + PG8_SB(b, h) + boff + n * 2048 + k * 1024); } while (0)
; #define PG8_MMA(ai, bj, At, Bt) do { __builtin_amdgcn_s_setprio(1); _Pragma("unroll") for (int m = 0; m < 4; ++m) _Pragma("unroll") for (int n = 0; n < 2; ++n) _Pragma("unroll") for (int k = 0; k < 2; ++k) \
;         acc[ai][bj][m][n] = __builtin_amdgcn_mfma_f32_16x16x32_bf16(Bt[n][k], At[m][k], acc[ai][bj][m][n], 0, 0, 0); __builtin_amdgcn_s_setprio(0); } while (0)
; #define PG8_WAIT_V(n) asm volatile("s_waitcnt vmcnt(" #n ")" ::: "memory")
; template <class Epi, class SchedT, bool ALIGN_EPI, bool SP2>
; __device__ __forceinline__ void gemm_phase(LAS unsigned char* lds, const int ldk, const int nt, const SchedT& S, const Epi& E) {
;     ...
;         for (int t = 0; t < nt; t += 2) {
;             const bool last = (t == nt - 2);
;             const char* a1 = cA + (size_t)(t + 1) * kstep;
;             const char* a2 = last ? nA : cA + (size_t)(t + 2) * kstep; const char* b2 = last ? nB : cB + (size_t)(t + 2) * kstep;
;             const char* a3 = a2 + kstep; const char* b3 = b2 + kstep;
;             if constexpr (SP2) {
;             PG8_LDB(B0, 0, 0); PG8_LDB(B1, 0, 1); PG8_SCHED; PG8_LDA(At, 0, 0); PG8_STAGE(PG8_SA(1, 1), a1 + hstep, voffA);
;             PG8_WAIT_V(8); PG8_WAIT_L(0); PG8_BAR; PG8_MMA(0, 0, At, B0); PG8_MMA(0, 1, At, B1); PG8_BAR; PG8_SCHED;
;     ...
;         for (int a = 0; a < 2; ++a)
; #pragma unroll
;             for (int b = 0; b < 2; ++b)
; #pragma unroll
;                 for (int m = 0; m < 4; ++m)
; #pragma unroll
;                     for (int n = 0; n < 2; ++n) acc[a][b][m][n] = (f32x4){0.f, 0.f, 0.f, 0.f};
;         }
;         cur = nxt; cA = nA; cB = nB; ++ui;
.LBB0_751:
	s_add_u32 s34, s34, 0x80080
	s_addc_u32 s35, s35, 0
	s_add_u32 s13, s36, 0x100
	v_mov_b32_e32 v2, 0
	s_addc_u32 s17, s37, 0
	s_mov_b32 s59, -2
	v_mov_b32_e32 v3, v2
	v_mov_b32_e32 v4, v2
	v_mov_b32_e32 v5, v2
	v_mov_b32_e32 v66, v2
	v_mov_b32_e32 v67, v2
	v_mov_b32_e32 v68, v2
	v_mov_b32_e32 v69, v2
	v_mov_b32_e32 v6, v2
	v_mov_b32_e32 v7, v2
	v_mov_b32_e32 v8, v2
	v_mov_b32_e32 v9, v2
	v_mov_b32_e32 v70, v2
	v_mov_b32_e32 v71, v2
	v_mov_b32_e32 v72, v2
	v_mov_b32_e32 v73, v2
	v_mov_b32_e32 v18, v2
	v_mov_b32_e32 v19, v2
	v_mov_b32_e32 v20, v2
	v_mov_b32_e32 v21, v2
	v_mov_b32_e32 v82, v2
	v_mov_b32_e32 v83, v2
	v_mov_b32_e32 v84, v2
	v_mov_b32_e32 v85, v2
	v_mov_b32_e32 v22, v2
	v_mov_b32_e32 v23, v2
	v_mov_b32_e32 v24, v2
	v_mov_b32_e32 v25, v2
	v_mov_b32_e32 v86, v2
	v_mov_b32_e32 v87, v2
	v_mov_b32_e32 v88, v2
	v_mov_b32_e32 v89, v2
	v_mov_b32_e32 v10, v2
	v_mov_b32_e32 v11, v2
	v_mov_b32_e32 v12, v2
	v_mov_b32_e32 v13, v2
	v_mov_b32_e32 v74, v2
	v_mov_b32_e32 v75, v2
	v_mov_b32_e32 v76, v2
	v_mov_b32_e32 v77, v2
	v_mov_b32_e32 v14, v2
	v_mov_b32_e32 v15, v2
	v_mov_b32_e32 v16, v2
	v_mov_b32_e32 v17, v2
	v_mov_b32_e32 v78, v2
	v_mov_b32_e32 v79, v2
	v_mov_b32_e32 v80, v2
	v_mov_b32_e32 v81, v2
	v_mov_b32_e32 v26, v2
	v_mov_b32_e32 v27, v2
	v_mov_b32_e32 v28, v2
	v_mov_b32_e32 v29, v2
	v_mov_b32_e32 v90, v2
	v_mov_b32_e32 v91, v2
	v_mov_b32_e32 v92, v2
	v_mov_b32_e32 v93, v2
	v_mov_b32_e32 v30, v2
	v_mov_b32_e32 v31, v2
	v_mov_b32_e32 v32, v2
	v_mov_b32_e32 v33, v2
	v_mov_b32_e32 v94, v2
	v_mov_b32_e32 v95, v2
	v_mov_b32_e32 v96, v2
	v_mov_b32_e32 v97, v2
	v_mov_b32_e32 v34, v2
	v_mov_b32_e32 v35, v2
	v_mov_b32_e32 v36, v2
	v_mov_b32_e32 v37, v2
	v_mov_b32_e32 v98, v2
	v_mov_b32_e32 v99, v2
	v_mov_b32_e32 v100, v2
	v_mov_b32_e32 v101, v2
	v_mov_b32_e32 v38, v2
	v_mov_b32_e32 v39, v2
	v_mov_b32_e32 v40, v2
	v_mov_b32_e32 v41, v2
	v_mov_b32_e32 v102, v2
	v_mov_b32_e32 v103, v2
	v_mov_b32_e32 v104, v2
	v_mov_b32_e32 v105, v2
	v_mov_b32_e32 v50, v2
	v_mov_b32_e32 v51, v2
	v_mov_b32_e32 v52, v2
	v_mov_b32_e32 v53, v2
	v_mov_b32_e32 v114, v2
	v_mov_b32_e32 v115, v2
	v_mov_b32_e32 v116, v2
	v_mov_b32_e32 v117, v2
	v_mov_b32_e32 v54, v2
	v_mov_b32_e32 v55, v2
	v_mov_b32_e32 v56, v2
	v_mov_b32_e32 v57, v2
	v_mov_b32_e32 v122, v2
	v_mov_b32_e32 v123, v2
	v_mov_b32_e32 v124, v2
	v_mov_b32_e32 v125, v2
	v_mov_b32_e32 v42, v2
	v_mov_b32_e32 v43, v2
	v_mov_b32_e32 v44, v2
	v_mov_b32_e32 v45, v2
	v_mov_b32_e32 v106, v2
	v_mov_b32_e32 v107, v2
	v_mov_b32_e32 v108, v2
	v_mov_b32_e32 v109, v2
	v_mov_b32_e32 v46, v2
	v_mov_b32_e32 v47, v2
	v_mov_b32_e32 v48, v2
	v_mov_b32_e32 v49, v2
	v_mov_b32_e32 v110, v2
	v_mov_b32_e32 v111, v2
	v_mov_b32_e32 v112, v2
	v_mov_b32_e32 v113, v2
	v_mov_b32_e32 v58, v2
	v_mov_b32_e32 v59, v2
	v_mov_b32_e32 v60, v2
	v_mov_b32_e32 v61, v2
	v_mov_b32_e32 v118, v2
	v_mov_b32_e32 v119, v2
	v_mov_b32_e32 v120, v2
	v_mov_b32_e32 v121, v2
	v_mov_b32_e32 v62, v2
	v_mov_b32_e32 v63, v2
	v_mov_b32_e32 v64, v2
	v_mov_b32_e32 v65, v2
	v_mov_b32_e32 v126, v2
	v_mov_b32_e32 v127, v2
	v_mov_b32_e32 v128, v2
	v_mov_b32_e32 v129, v2
	s_add_u32 s36, s34, 0xfff7ff80
	s_addc_u32 s37, s35, -1
	v_lshl_add_u64 v[222:223], s[36:37], 0, v[146:147]
	v_lshl_add_u64 v[224:225], s[36:37], 0, v[148:149]
.LBB0_752:
	s_add_u32 s36, s34, 0xfff80080
	s_addc_u32 s37, s35, -1
	s_add_i32 s61, 0, 0x10000
	s_cmp_eq_u32 s59, 28
	s_cselect_b32 vcc_hi, s1, s37
	s_cselect_b32 vcc_lo, s0, s36
	s_cselect_b32 s37, s63, s17
	s_cselect_b32 s36, s62, s13
	s_add_i32 s64, 0, 0x14000
	v_add_u32_e32 v142, s61, v248
	v_add_u32_e32 v182, s64, v248
	ds_read_b128 v[130:133], v142
	ds_read_b128 v[134:137], v142 offset:1024
	ds_read_b128 v[138:141], v142 offset:2048
	ds_read_b128 v[142:145], v142 offset:3072
	ds_read_b128 v[158:161], v182
	ds_read_b128 v[174:177], v182 offset:1024
	ds_read_b128 v[178:181], v182 offset:2048
	ds_read_b128 v[182:185], v182 offset:3072
	v_lshl_add_u64 v[218:219], v[222:223], 0, s[24:25]
	s_mov_b32 m0, s89
	s_nop 0
	global_load_lds_dwordx4 v[218:219], off
	v_lshl_add_u64 v[218:219], v[224:225], 0, s[24:25]
	s_mov_b32 m0, s90
	s_nop 0
	global_load_lds_dwordx4 v[218:219], off
	v_lshl_add_u64 v[218:219], s[34:35], 0, v[154:155]
	s_add_i32 m0, s85, 0xc000
	ds_read_b128 v[186:189], v251
	ds_read_b128 v[190:193], v251 offset:1024
	ds_read_b128 v[194:197], v251 offset:2048
	ds_read_b128 v[198:201], v251 offset:3072
	ds_read_b128 v[202:205], v251 offset:4096
	ds_read_b128 v[206:209], v251 offset:5120
	ds_read_b128 v[210:213], v251 offset:6144
	ds_read_b128 v[214:217], v251 offset:7168
	global_load_lds_dwordx4 v[218:219], off
	v_lshl_add_u64 v[218:219], s[34:35], 0, v[156:157]
	s_add_i32 m0, s85, 0xe000
	s_nop 0
	global_load_lds_dwordx4 v[218:219], off
	s_waitcnt vmcnt(8)
	s_waitcnt lgkmcnt(0)
	s_barrier
; #define PG8_STAGE(bufoff, gbase, voff) do { _Pragma("unroll") for (int _i = 0; _i < 2; ++_i) \
;         __builtin_amdgcn_global_load_lds((const __attribute__((address_space(1))) unsigned*)((const char*)(gbase) + (voff)[_i]), (LAS unsigned*)(lds + (bufoff) + ldsw + _i * 8192), 16, 0, 0); } while (0)
; #define PG8_LDA(dst, b, h) do { _Pragma("unroll") for (int m = 0; m < 4; ++m) _Pragma("unroll") for (int k = 0; k < 2; ++k) dst[m][k] = *(const LAS bf16x8*)(lds + PG8_SA(b, h) + aoff + m * 2048 + k * 1024); } while (0)
; #define PG8_MMA(ai, bj, At, Bt) do { __builtin_amdgcn_s_setprio(1); _Pragma("unroll") for (int m = 0; m < 4; ++m) _Pragma("unroll") for (int n = 0; n < 2; ++n) _Pragma("unroll") for (int k = 0; k < 2; ++k) \
;         acc[ai][bj][m][n] = __builtin_amdgcn_mfma_f32_16x16x32_bf16(Bt[n][k], At[m][k], acc[ai][bj][m][n], 0, 0, 0); __builtin_amdgcn_s_setprio(0); } while (0)
; #define PG8_WAIT_V(n) asm volatile("s_waitcnt vmcnt(" #n ")" ::: "memory")
; #define PG8_WAIT_L(n) asm volatile("s_waitcnt lgkmcnt(" #n ")" ::: "memory")
; #define PG8_BAR __builtin_amdgcn_s_barrier()
; #define PG8_SCHED __builtin_amdgcn_sched_barrier(0)
; template <class Epi, class SchedT, bool ALIGN_EPI, bool SP2>
; __device__ __forceinline__ void gemm_phase(LAS unsigned char* lds, const int ldk, const int nt, const SchedT& S, const Epi& E) {
;     ...
;             PG8_WAIT_V(8); PG8_WAIT_L(0); PG8_BAR; PG8_MMA(0, 0, At, B0); PG8_MMA(0, 1, At, B1); PG8_BAR; PG8_SCHED;
;             PG8_LDA(At, 0, 1); PG8_STAGE(PG8_SB(0, 0), b2, voffB); PG8_STAGE(PG8_SB(0, 1), b2 + hstepB, voffB); PG8_STAGE(PG8_SA(0, 0), a2, voffA);
;             PG8_WAIT_V(8); PG8_WAIT_L(0); PG8_BAR; PG8_MMA(1, 0, At, B0); PG8_MMA(1, 1, At, B1); PG8_BAR; PG8_SCHED;
	s_setprio 1
	s_waitcnt lgkmcnt(0)
	v_mfma_f32_16x16x32_bf16 v[126:129], v[130:133], v[186:189], v[126:129]
	v_mfma_f32_16x16x32_bf16 v[62:65], v[138:141], v[186:189], v[62:65]
	v_mfma_f32_16x16x32_bf16 v[118:121], v[130:133], v[194:197], v[118:121]
	v_mfma_f32_16x16x32_bf16 v[58:61], v[138:141], v[194:197], v[58:61]
	v_mfma_f32_16x16x32_bf16 v[110:113], v[130:133], v[202:205], v[110:113]
	v_mfma_f32_16x16x32_bf16 v[46:49], v[138:141], v[202:205], v[46:49]
	v_mfma_f32_16x16x32_bf16 v[106:109], v[130:133], v[210:213], v[106:109]
	v_mfma_f32_16x16x32_bf16 v[42:45], v[138:141], v[210:213], v[42:45]
	v_mfma_f32_16x16x32_bf16 v[126:129], v[134:137], v[190:193], v[126:129]
	v_mfma_f32_16x16x32_bf16 v[62:65], v[142:145], v[190:193], v[62:65]
	v_mfma_f32_16x16x32_bf16 v[118:121], v[134:137], v[198:201], v[118:121]
	v_mfma_f32_16x16x32_bf16 v[58:61], v[142:145], v[198:201], v[58:61]
	v_mfma_f32_16x16x32_bf16 v[110:113], v[134:137], v[206:209], v[110:113]
	v_mfma_f32_16x16x32_bf16 v[46:49], v[142:145], v[206:209], v[46:49]
	v_mfma_f32_16x16x32_bf16 v[106:109], v[134:137], v[214:217], v[106:109]
	v_mfma_f32_16x16x32_bf16 v[42:45], v[142:145], v[214:217], v[42:45]
	s_setprio 0
	s_setprio 1
	v_mfma_f32_16x16x32_bf16 v[122:125], v[158:161], v[186:189], v[122:125]
	v_mfma_f32_16x16x32_bf16 v[54:57], v[178:181], v[186:189], v[54:57]
	v_mfma_f32_16x16x32_bf16 v[114:117], v[158:161], v[194:197], v[114:117]
	v_mfma_f32_16x16x32_bf16 v[50:53], v[178:181], v[194:197], v[50:53]
	v_mfma_f32_16x16x32_bf16 v[102:105], v[158:161], v[202:205], v[102:105]
	v_mfma_f32_16x16x32_bf16 v[38:41], v[178:181], v[202:205], v[38:41]
	v_mfma_f32_16x16x32_bf16 v[98:101], v[158:161], v[210:213], v[98:101]
	v_mfma_f32_16x16x32_bf16 v[34:37], v[178:181], v[210:213], v[34:37]
	v_mfma_f32_16x16x32_bf16 v[122:125], v[174:177], v[190:193], v[122:125]
	v_mfma_f32_16x16x32_bf16 v[54:57], v[182:185], v[190:193], v[54:57]
	v_mfma_f32_16x16x32_bf16 v[114:117], v[174:177], v[198:201], v[114:117]
	v_mfma_f32_16x16x32_bf16 v[50:53], v[182:185], v[198:201], v[50:53]
	v_mfma_f32_16x16x32_bf16 v[102:105], v[174:177], v[206:209], v[102:105]
	v_mfma_f32_16x16x32_bf16 v[38:41], v[182:185], v[206:209], v[38:41]
	v_mfma_f32_16x16x32_bf16 v[98:101], v[174:177], v[214:217], v[98:101]
	v_mfma_f32_16x16x32_bf16 v[34:37], v[182:185], v[214:217], v[34:37]
	s_setprio 0
	s_barrier
	s_add_i32 s61, s61, s84
	v_lshl_add_u64 v[218:219], s[36:37], 0, v[0:1]
	s_mov_b32 m0, s61
	ds_read_b128 v[186:189], v251 offset:16384
	ds_read_b128 v[190:193], v251 offset:17408
	ds_read_b128 v[194:197], v251 offset:18432
	ds_read_b128 v[198:201], v251 offset:19456
	ds_read_b128 v[202:205], v251 offset:20480
	ds_read_b128 v[206:209], v251 offset:21504
	ds_read_b128 v[210:213], v251 offset:22528
	ds_read_b128 v[214:217], v251 offset:23552
	global_load_lds_dwordx4 v[218:219], off
	s_add_i32 m0, s61, 0x2000
	s_add_u32 s94, s36, 0x20000
	v_lshl_add_u64 v[220:221], s[36:37], 0, v[150:151]
	s_addc_u32 s95, s37, 0
	s_add_i32 s61, s64, s84
	global_load_lds_dwordx4 v[220:221], off
	v_lshl_add_u64 v[222:223], s[94:95], 0, v[0:1]
	s_mov_b32 m0, s61
	v_lshl_add_u64 v[224:225], vcc, 0, v[148:149]
	global_load_lds_dwordx4 v[222:223], off
	v_lshl_add_u64 v[222:223], s[94:95], 0, v[150:151]
	s_add_i32 m0, s61, 0x2000
	s_nop 0
	global_load_lds_dwordx4 v[222:223], off
	v_lshl_add_u64 v[222:223], vcc, 0, v[146:147]
	s_waitcnt vmcnt(6)
	s_waitcnt lgkmcnt(0)
	s_barrier
	s_setprio 1
	s_waitcnt lgkmcnt(0)
	v_mfma_f32_16x16x32_bf16 v[94:97], v[130:133], v[186:189], v[94:97]
	v_mfma_f32_16x16x32_bf16 v[30:33], v[138:141], v[186:189], v[30:33]
	v_mfma_f32_16x16x32_bf16 v[90:93], v[130:133], v[194:197], v[90:93]
	v_mfma_f32_16x16x32_bf16 v[26:29], v[138:141], v[194:197], v[26:29]
	v_mfma_f32_16x16x32_bf16 v[78:81], v[130:133], v[202:205], v[78:81]
	v_mfma_f32_16x16x32_bf16 v[14:17], v[138:141], v[202:205], v[14:17]
	v_mfma_f32_16x16x32_bf16 v[74:77], v[130:133], v[210:213], v[74:77]
	v_mfma_f32_16x16x32_bf16 v[10:13], v[138:141], v[210:213], v[10:13]
	v_mfma_f32_16x16x32_bf16 v[94:97], v[134:137], v[190:193], v[94:97]
	v_mfma_f32_16x16x32_bf16 v[30:33], v[142:145], v[190:193], v[30:33]
	v_mfma_f32_16x16x32_bf16 v[90:93], v[134:137], v[198:201], v[90:93]
	v_mfma_f32_16x16x32_bf16 v[26:29], v[142:145], v[198:201], v[26:29]
	v_mfma_f32_16x16x32_bf16 v[78:81], v[134:137], v[206:209], v[78:81]
	v_mfma_f32_16x16x32_bf16 v[14:17], v[142:145], v[206:209], v[14:17]
	v_mfma_f32_16x16x32_bf16 v[74:77], v[134:137], v[214:217], v[74:77]
	v_mfma_f32_16x16x32_bf16 v[10:13], v[142:145], v[214:217], v[10:13]
	s_setprio 0
	s_setprio 1
	v_mfma_f32_16x16x32_bf16 v[86:89], v[158:161], v[186:189], v[86:89]
	v_mfma_f32_16x16x32_bf16 v[22:25], v[178:181], v[186:189], v[22:25]
	v_mfma_f32_16x16x32_bf16 v[82:85], v[158:161], v[194:197], v[82:85]
	v_mfma_f32_16x16x32_bf16 v[18:21], v[178:181], v[194:197], v[18:21]
	v_mfma_f32_16x16x32_bf16 v[70:73], v[158:161], v[202:205], v[70:73]
	v_mfma_f32_16x16x32_bf16 v[6:9], v[178:181], v[202:205], v[6:9]
	v_mfma_f32_16x16x32_bf16 v[66:69], v[158:161], v[210:213], v[66:69]
	v_mfma_f32_16x16x32_bf16 v[2:5], v[178:181], v[210:213], v[2:5]
	v_mfma_f32_16x16x32_bf16 v[86:89], v[174:177], v[190:193], v[86:89]
	v_mfma_f32_16x16x32_bf16 v[22:25], v[182:185], v[190:193], v[22:25]
	v_mfma_f32_16x16x32_bf16 v[82:85], v[174:177], v[198:201], v[82:85]
	v_mfma_f32_16x16x32_bf16 v[18:21], v[182:185], v[198:201], v[18:21]
	v_mfma_f32_16x16x32_bf16 v[70:73], v[174:177], v[206:209], v[70:73]
	v_mfma_f32_16x16x32_bf16 v[6:9], v[182:185], v[206:209], v[6:9]
	v_mfma_f32_16x16x32_bf16 v[66:69], v[174:177], v[214:217], v[66:69]
	v_mfma_f32_16x16x32_bf16 v[2:5], v[182:185], v[214:217], v[2:5]
	s_setprio 0
	s_barrier
; #define PG8_STAGE(bufoff, gbase, voff) do { _Pragma("unroll") for (int _i = 0; _i < 2; ++_i) \
;         __builtin_amdgcn_global_load_lds((const __attribute__((address_space(1))) unsigned*)((const char*)(gbase) + (voff)[_i]), (LAS unsigned*)(lds + (bufoff) + ldsw + _i * 8192), 16, 0, 0); } while (0)
; #define PG8_LDA(dst, b, h) do { _Pragma("unroll") for (int m = 0; m < 4; ++m) _Pragma("unroll") for (int k = 0; k < 2; ++k) dst[m][k] = *(const LAS bf16x8*)(lds + PG8_SA(b, h) + aoff + m * 2048 + k * 1024); } while (0)
; #define PG8_LDB(dst, b, h) do { _Pragma("unroll") for (int n = 0; n < 2; ++n) _Pragma("unroll") for (int k = 0; k < 2; ++k) dst[n][k] = *(const LAS bf16x8*)(lds + PG8_SB(b, h) + boff + n * 2048 + k * 1024); } while (0)
; #define PG8_MMA(ai, bj, At, Bt) do { __builtin_amdgcn_s_setprio(1); _Pragma("unroll") for (int m = 0; m < 4; ++m) _Pragma("unroll") for (int n = 0; n < 2; ++n) _Pragma("unroll") for (int k = 0; k < 2; ++k) \
;         acc[ai][bj][m][n] = __builtin_amdgcn_mfma_f32_16x16x32_bf16(Bt[n][k], At[m][k], acc[ai][bj][m][n], 0, 0, 0); __builtin_amdgcn_s_setprio(0); } while (0)
; #define PG8_WAIT_V(n) asm volatile("s_waitcnt vmcnt(" #n ")" ::: "memory")
; #define PG8_WAIT_L(n) asm volatile("s_waitcnt lgkmcnt(" #n ")" ::: "memory")
; #define PG8_BAR __builtin_amdgcn_s_barrier()
; #define PG8_SCHED __builtin_amdgcn_sched_barrier(0)
; template <class Epi, class SchedT, bool ALIGN_EPI, bool SP2>
; __device__ __forceinline__ void gemm_phase(LAS unsigned char* lds, const int ldk, const int nt, const SchedT& S, const Epi& E) {
;     ...
;             PG8_WAIT_V(8); PG8_WAIT_L(0); PG8_BAR; PG8_MMA(1, 0, At, B0); PG8_MMA(1, 1, At, B1); PG8_BAR; PG8_SCHED;
;             PG8_LDB(B0, 1, 0); PG8_LDB(B1, 1, 1); PG8_SCHED; PG8_LDA(At, 1, 0); PG8_STAGE(PG8_SA(0, 1), a2 + hstep, voffA);
;             PG8_WAIT_V(8); PG8_WAIT_L(0); PG8_BAR; PG8_MMA(0, 0, At, B0); PG8_MMA(0, 1, At, B1); PG8_BAR; PG8_SCHED;
	s_add_i32 s61, 0, 0x18000
	s_add_i32 s64, 0, 0x1c000
	v_add_u32_e32 v142, s61, v248
	v_add_u32_e32 v182, s64, v248
	ds_read_b128 v[130:133], v142
	ds_read_b128 v[134:137], v142 offset:1024
	ds_read_b128 v[138:141], v142 offset:2048
	ds_read_b128 v[142:145], v142 offset:3072
	ds_read_b128 v[158:161], v182
	ds_read_b128 v[174:177], v182 offset:1024
	ds_read_b128 v[178:181], v182 offset:2048
	ds_read_b128 v[182:185], v182 offset:3072
	s_add_u32 s94, vcc_lo, 0x80000
	s_addc_u32 s95, vcc_hi, 0
	s_mov_b32 m0, s85
	s_nop 0
	global_load_lds_dwordx4 v[222:223], off
	s_mov_b32 m0, s86
	s_nop 0
	global_load_lds_dwordx4 v[224:225], off
	s_mov_b32 m0, s87
	v_lshl_add_u64 v[226:227], s[94:95], 0, v[146:147]
	ds_read_b128 v[186:189], v251 offset:32768
	ds_read_b128 v[190:193], v251 offset:33792
	ds_read_b128 v[194:197], v251 offset:34816
	ds_read_b128 v[198:201], v251 offset:35840
	ds_read_b128 v[202:205], v251 offset:36864
	ds_read_b128 v[206:209], v251 offset:37888
	ds_read_b128 v[210:213], v251 offset:38912
	ds_read_b128 v[214:217], v251 offset:39936
	global_load_lds_dwordx4 v[226:227], off
	v_lshl_add_u64 v[226:227], s[94:95], 0, v[148:149]
	s_mov_b32 m0, s88
	s_nop 0
	global_load_lds_dwordx4 v[226:227], off
	s_waitcnt vmcnt(8)
	s_waitcnt lgkmcnt(0)
	s_barrier
	s_setprio 1
	s_waitcnt lgkmcnt(0)
	v_mfma_f32_16x16x32_bf16 v[126:129], v[130:133], v[186:189], v[126:129]
	v_mfma_f32_16x16x32_bf16 v[62:65], v[138:141], v[186:189], v[62:65]
	v_mfma_f32_16x16x32_bf16 v[118:121], v[130:133], v[194:197], v[118:121]
	v_mfma_f32_16x16x32_bf16 v[58:61], v[138:141], v[194:197], v[58:61]
	v_mfma_f32_16x16x32_bf16 v[110:113], v[130:133], v[202:205], v[110:113]
	v_mfma_f32_16x16x32_bf16 v[46:49], v[138:141], v[202:205], v[46:49]
	v_mfma_f32_16x16x32_bf16 v[106:109], v[130:133], v[210:213], v[106:109]
	v_mfma_f32_16x16x32_bf16 v[42:45], v[138:141], v[210:213], v[42:45]
	v_mfma_f32_16x16x32_bf16 v[126:129], v[134:137], v[190:193], v[126:129]
	v_mfma_f32_16x16x32_bf16 v[62:65], v[142:145], v[190:193], v[62:65]
	v_mfma_f32_16x16x32_bf16 v[118:121], v[134:137], v[198:201], v[118:121]
	v_mfma_f32_16x16x32_bf16 v[58:61], v[142:145], v[198:201], v[58:61]
	v_mfma_f32_16x16x32_bf16 v[110:113], v[134:137], v[206:209], v[110:113]
	v_mfma_f32_16x16x32_bf16 v[46:49], v[142:145], v[206:209], v[46:49]
	v_mfma_f32_16x16x32_bf16 v[106:109], v[134:137], v[214:217], v[106:109]
	v_mfma_f32_16x16x32_bf16 v[42:45], v[142:145], v[214:217], v[42:45]
	s_setprio 0
	s_setprio 1
	v_mfma_f32_16x16x32_bf16 v[122:125], v[158:161], v[186:189], v[122:125]
	v_mfma_f32_16x16x32_bf16 v[54:57], v[178:181], v[186:189], v[54:57]
	v_mfma_f32_16x16x32_bf16 v[114:117], v[158:161], v[194:197], v[114:117]
	v_mfma_f32_16x16x32_bf16 v[50:53], v[178:181], v[194:197], v[50:53]
	v_mfma_f32_16x16x32_bf16 v[102:105], v[158:161], v[202:205], v[102:105]
	v_mfma_f32_16x16x32_bf16 v[38:41], v[178:181], v[202:205], v[38:41]
	v_mfma_f32_16x16x32_bf16 v[98:101], v[158:161], v[210:213], v[98:101]
	v_mfma_f32_16x16x32_bf16 v[34:37], v[178:181], v[210:213], v[34:37]
	v_mfma_f32_16x16x32_bf16 v[122:125], v[174:177], v[190:193], v[122:125]
	v_mfma_f32_16x16x32_bf16 v[54:57], v[182:185], v[190:193], v[54:57]
	v_mfma_f32_16x16x32_bf16 v[114:117], v[174:177], v[198:201], v[114:117]
	v_mfma_f32_16x16x32_bf16 v[50:53], v[182:185], v[198:201], v[50:53]
	v_mfma_f32_16x16x32_bf16 v[102:105], v[174:177], v[206:209], v[102:105]
	v_mfma_f32_16x16x32_bf16 v[38:41], v[182:185], v[206:209], v[38:41]
	v_mfma_f32_16x16x32_bf16 v[98:101], v[174:177], v[214:217], v[98:101]
	v_mfma_f32_16x16x32_bf16 v[34:37], v[182:185], v[214:217], v[34:37]
	s_setprio 0
	s_barrier
; #define PG8_STAGE(bufoff, gbase, voff) do { _Pragma("unroll") for (int _i = 0; _i < 2; ++_i) \
;         __builtin_amdgcn_global_load_lds((const __attribute__((address_space(1))) unsigned*)((const char*)(gbase) + (voff)[_i]), (LAS unsigned*)(lds + (bufoff) + ldsw + _i * 8192), 16, 0, 0); } while (0)
; #define PG8_LDA(dst, b, h) do { _Pragma("unroll") for (int m = 0; m < 4; ++m) _Pragma("unroll") for (int k = 0; k < 2; ++k) dst[m][k] = *(const LAS bf16x8*)(lds + PG8_SA(b, h) + aoff + m * 2048 + k * 1024); } while (0)
; #define PG8_MMA(ai, bj, At, Bt) do { __builtin_amdgcn_s_setprio(1); _Pragma("unroll") for (int m = 0; m < 4; ++m) _Pragma("unroll") for (int n = 0; n < 2; ++n) _Pragma("unroll") for (int k = 0; k < 2; ++k) \
;         acc[ai][bj][m][n] = __builtin_amdgcn_mfma_f32_16x16x32_bf16(Bt[n][k], At[m][k], acc[ai][bj][m][n], 0, 0, 0); __builtin_amdgcn_s_setprio(0); } while (0)
; #define PG8_WAIT_V(n) asm volatile("s_waitcnt vmcnt(" #n ")" ::: "memory")
; #define PG8_WAIT_L(n) asm volatile("s_waitcnt lgkmcnt(" #n ")" ::: "memory")
; #define PG8_BAR __builtin_amdgcn_s_barrier()
; #define PG8_SCHED __builtin_amdgcn_sched_barrier(0)
; template <class Epi, class SchedT, bool ALIGN_EPI, bool SP2>
; __device__ __forceinline__ void gemm_phase(LAS unsigned char* lds, const int ldk, const int nt, const SchedT& S, const Epi& E) {
;     ...
;             PG8_WAIT_V(8); PG8_WAIT_L(0); PG8_BAR; PG8_MMA(0, 0, At, B0); PG8_MMA(0, 1, At, B1); PG8_BAR; PG8_SCHED;
;             PG8_LDA(At, 1, 1); PG8_STAGE(PG8_SB(1, 0), b3, voffB); PG8_STAGE(PG8_SB(1, 1), b3 + hstepB, voffB); PG8_STAGE(PG8_SA(1, 0), a3, voffA);
;             PG8_WAIT_V(8); PG8_WAIT_L(0); PG8_BAR; PG8_MMA(1, 0, At, B0); PG8_MMA(1, 1, At, B1); PG8_BAR; PG8_SCHED;
	s_add_i32 s61, s61, s84
	v_lshl_add_u64 v[218:219], v[218:219], 0, s[24:25]
	s_mov_b32 m0, s61
	ds_read_b128 v[186:189], v251 offset:49152
	ds_read_b128 v[190:193], v251 offset:50176
	ds_read_b128 v[194:197], v251 offset:51200
	ds_read_b128 v[198:201], v251 offset:52224
	ds_read_b128 v[202:205], v251 offset:53248
	ds_read_b128 v[206:209], v251 offset:54272
	ds_read_b128 v[210:213], v251 offset:55296
	ds_read_b128 v[214:217], v251 offset:56320
	global_load_lds_dwordx4 v[218:219], off
	s_add_i32 m0, s61, 0x2000
	s_add_u32 s36, s36, 0x20080
	v_lshl_add_u64 v[218:219], v[220:221], 0, s[24:25]
	s_addc_u32 s37, s37, 0
	s_add_i32 s61, s64, s84
	global_load_lds_dwordx4 v[218:219], off
	v_lshl_add_u64 v[218:219], s[36:37], 0, v[0:1]
	s_mov_b32 m0, s61
	s_nop 0
	global_load_lds_dwordx4 v[218:219], off
	v_lshl_add_u64 v[218:219], s[36:37], 0, v[150:151]
	s_add_i32 m0, s61, 0x2000
	s_nop 0
	global_load_lds_dwordx4 v[218:219], off
	s_waitcnt vmcnt(6)
	s_waitcnt lgkmcnt(0)
	s_barrier
	s_setprio 1
	s_waitcnt lgkmcnt(0)
	v_mfma_f32_16x16x32_bf16 v[94:97], v[130:133], v[186:189], v[94:97]
	v_mfma_f32_16x16x32_bf16 v[30:33], v[138:141], v[186:189], v[30:33]
	v_mfma_f32_16x16x32_bf16 v[90:93], v[130:133], v[194:197], v[90:93]
	v_mfma_f32_16x16x32_bf16 v[26:29], v[138:141], v[194:197], v[26:29]
	v_mfma_f32_16x16x32_bf16 v[78:81], v[130:133], v[202:205], v[78:81]
	v_mfma_f32_16x16x32_bf16 v[14:17], v[138:141], v[202:205], v[14:17]
	v_mfma_f32_16x16x32_bf16 v[74:77], v[130:133], v[210:213], v[74:77]
	v_mfma_f32_16x16x32_bf16 v[10:13], v[138:141], v[210:213], v[10:13]
	v_mfma_f32_16x16x32_bf16 v[94:97], v[134:137], v[190:193], v[94:97]
	v_mfma_f32_16x16x32_bf16 v[30:33], v[142:145], v[190:193], v[30:33]
	v_mfma_f32_16x16x32_bf16 v[90:93], v[134:137], v[198:201], v[90:93]
	v_mfma_f32_16x16x32_bf16 v[26:29], v[142:145], v[198:201], v[26:29]
	v_mfma_f32_16x16x32_bf16 v[78:81], v[134:137], v[206:209], v[78:81]
	v_mfma_f32_16x16x32_bf16 v[14:17], v[142:145], v[206:209], v[14:17]
	v_mfma_f32_16x16x32_bf16 v[74:77], v[134:137], v[214:217], v[74:77]
	v_mfma_f32_16x16x32_bf16 v[10:13], v[142:145], v[214:217], v[10:13]
	s_setprio 0
	s_setprio 1
	v_mfma_f32_16x16x32_bf16 v[86:89], v[158:161], v[186:189], v[86:89]
	v_mfma_f32_16x16x32_bf16 v[22:25], v[178:181], v[186:189], v[22:25]
	v_mfma_f32_16x16x32_bf16 v[82:85], v[158:161], v[194:197], v[82:85]
	v_mfma_f32_16x16x32_bf16 v[18:21], v[178:181], v[194:197], v[18:21]
	v_mfma_f32_16x16x32_bf16 v[70:73], v[158:161], v[202:205], v[70:73]
	v_mfma_f32_16x16x32_bf16 v[6:9], v[178:181], v[202:205], v[6:9]
	v_mfma_f32_16x16x32_bf16 v[66:69], v[158:161], v[210:213], v[66:69]
	v_mfma_f32_16x16x32_bf16 v[2:5], v[178:181], v[210:213], v[2:5]
	v_mfma_f32_16x16x32_bf16 v[86:89], v[174:177], v[190:193], v[86:89]
	v_mfma_f32_16x16x32_bf16 v[22:25], v[182:185], v[190:193], v[22:25]
	v_mfma_f32_16x16x32_bf16 v[82:85], v[174:177], v[198:201], v[82:85]
	v_mfma_f32_16x16x32_bf16 v[18:21], v[182:185], v[198:201], v[18:21]
	v_mfma_f32_16x16x32_bf16 v[70:73], v[174:177], v[206:209], v[70:73]
	v_mfma_f32_16x16x32_bf16 v[6:9], v[182:185], v[206:209], v[6:9]
	v_mfma_f32_16x16x32_bf16 v[66:69], v[174:177], v[214:217], v[66:69]
	v_mfma_f32_16x16x32_bf16 v[2:5], v[182:185], v[214:217], v[2:5]
	s_setprio 0
	s_barrier
	s_add_i32 s59, s59, 2
	s_add_u32 s34, s34, 0x100
	s_addc_u32 s35, s35, 0
	s_add_u32 s13, s13, 0x100
	s_addc_u32 s17, s17, 0
	s_cmp_gt_u32 s59, 29
	s_cbranch_scc0 .LBB0_752
	s_and_b64 vcc, exec, s[56:57]
	s_cbranch_vccz .LBB0_755
	s_barrier
